# v46 + nt (non-temporal) on the once-read 16-byte loads of P0 (x rows and FFN1 weights) - strategy: cache policy for streamed once-read inputs
# speedup vs baseline: 1.0161x; 1.0161x over previous
.LBB0_14:
	s_cmpk_gt_i32 s38, 0x57f
	s_mov_b64 s[0:1], -1
	s_cbranch_scc0 .LBB0_28
	s_cmpk_gt_u32 s38, 0xaff
	s_cbranch_scc0 .LBB0_17
	s_add_i32 s1, s14, 0xfffea000
	s_and_b32 s0, s20, 0xfc0
	s_and_b32 s1, s1, 0x3e0
	v_or_b32_e32 v4, s0, v34
	s_lshl_b32 s6, s1, 2
	v_lshl_add_u64 v[2:3], v[42:43], 0, s[6:7]
	v_lshlrev_b32_e32 v36, 12, v4
	v_lshl_add_u64 v[26:27], v[2:3], 0, v[36:37]
	v_add_co_u32_e32 v6, vcc, s22, v26
	v_or_b32_e32 v36, s1, v34
	s_nop 0
	v_addc_co_u32_e32 v7, vcc, 0, v27, vcc
	v_add_co_u32_e32 v10, vcc, s23, v26
	global_load_dwordx4 v[2:5], v[26:27], off nt
	s_nop 0
	global_load_dwordx4 v[6:9], v[6:7], off nt
	v_addc_co_u32_e32 v11, vcc, 0, v27, vcc
	v_add_co_u32_e32 v14, vcc, s24, v26
	v_or_b32_e32 v48, s1, v50
	s_nop 0
	v_addc_co_u32_e32 v15, vcc, 0, v27, vcc
	v_add_co_u32_e32 v18, vcc, s25, v26
	global_load_dwordx4 v[10:13], v[10:11], off nt
	s_nop 0
	global_load_dwordx4 v[14:17], v[14:15], off nt
	v_addc_co_u32_e32 v19, vcc, 0, v27, vcc
	v_add_co_u32_e32 v22, vcc, s26, v26
	v_or_b32_e32 v49, s1, v51
	s_nop 0
	v_addc_co_u32_e32 v23, vcc, 0, v27, vcc
	v_add_co_u32_e32 v28, vcc, s27, v26
	global_load_dwordx4 v[18:21], v[18:19], off nt
	s_nop 0
	global_load_dwordx4 v[22:25], v[22:23], off nt
	v_addc_co_u32_e32 v29, vcc, 0, v27, vcc
	v_add_co_u32_e32 v30, vcc, s28, v26
	s_lshl_b32 s6, s0, 1
	s_nop 0
	v_addc_co_u32_e32 v31, vcc, 0, v27, vcc
	global_load_dwordx4 v[26:29], v[28:29], off nt
	s_nop 0
	global_load_dwordx4 v[30:33], v[30:31], off nt
	v_mul_u32_u24_e32 v36, 0xb00, v36
	v_mul_u32_u24_e32 v62, 0xb00, v48
	v_mul_u32_u24_e32 v64, 0xb00, v49
	v_lshl_add_u64 v[48:49], v[38:39], 0, s[6:7]
	v_lshlrev_b32_e32 v36, 1, v36
	v_lshl_add_u64 v[60:61], v[48:49], 0, v[36:37]
	v_lshlrev_b32_e32 v36, 1, v62
	v_lshl_add_u64 v[62:63], v[48:49], 0, v[36:37]
	v_lshlrev_b32_e32 v36, 1, v64
	s_waitcnt vmcnt(6)
	ds_write2_b32 v1, v2, v6 offset1:8
	ds_write2_b32 v1, v3, v7 offset0:66 offset1:74
	ds_write2_b32 v1, v4, v8 offset0:132 offset1:140
	ds_write2_b32 v1, v5, v9 offset0:198 offset1:206
	s_waitcnt vmcnt(4)
	ds_write2_b32 v1, v10, v14 offset0:16 offset1:24
	ds_write2_b32 v1, v11, v15 offset0:82 offset1:90
	ds_write2_b32 v1, v12, v16 offset0:148 offset1:156
	ds_write2_b32 v1, v13, v17 offset0:214 offset1:222
	s_waitcnt vmcnt(2)
	ds_write2_b32 v1, v18, v22 offset0:32 offset1:40
	ds_write2_b32 v1, v19, v23 offset0:98 offset1:106
	ds_write2_b32 v1, v20, v24 offset0:164 offset1:172
	ds_write2_b32 v1, v21, v25 offset0:230 offset1:238
	s_waitcnt vmcnt(0)
	ds_write2_b32 v1, v26, v30 offset0:48 offset1:56
	ds_write2_b32 v1, v27, v31 offset0:114 offset1:122
	ds_write2_b32 v1, v28, v32 offset0:180 offset1:188
	ds_write2_b32 v1, v29, v33 offset0:246 offset1:254
	s_waitcnt lgkmcnt(0)
	ds_read2_b64 v[2:5], v53 offset1:1
	ds_read2_b64 v[6:9], v53 offset0:2 offset1:3
	ds_read2_b64 v[10:13], v54 offset1:1
	ds_read2_b64 v[14:17], v55 offset1:1
	ds_read2_b64 v[18:21], v56 offset1:1
	ds_read2_b64 v[22:25], v57 offset1:1
	ds_read2_b64 v[26:29], v58 offset1:1
	s_waitcnt lgkmcnt(6)
	v_cvt_pk_bf16_f32 v2, v2, v3
	v_cvt_pk_bf16_f32 v3, v4, v5
	s_waitcnt lgkmcnt(5)
	v_cvt_pk_bf16_f32 v4, v6, v7
	v_cvt_pk_bf16_f32 v5, v8, v9
	s_waitcnt lgkmcnt(4)
	v_cvt_pk_bf16_f32 v6, v10, v11
	v_cvt_pk_bf16_f32 v7, v12, v13
	s_waitcnt lgkmcnt(3)
	v_cvt_pk_bf16_f32 v8, v14, v15
	v_cvt_pk_bf16_f32 v9, v16, v17
	global_store_dwordx4 v[60:61], v[2:5], off sc0 sc1
	global_store_dwordx4 v[62:63], v[6:9], off sc0 sc1
	ds_read2_b64 v[2:5], v59 offset1:1
	s_waitcnt lgkmcnt(3)
	v_cvt_pk_bf16_f32 v10, v18, v19
	v_cvt_pk_bf16_f32 v11, v20, v21
	s_waitcnt lgkmcnt(2)
	v_cvt_pk_bf16_f32 v12, v22, v23
	v_cvt_pk_bf16_f32 v13, v24, v25
	s_waitcnt lgkmcnt(0)
	v_cvt_pk_bf16_f32 v8, v2, v3
	v_or_b32_e32 v2, s1, v52
	v_mul_u32_u24_e32 v2, 0xb00, v2
	v_lshl_add_u64 v[6:7], v[48:49], 0, v[36:37]
	v_lshlrev_b32_e32 v36, 1, v2
	global_store_dwordx4 v[6:7], v[10:13], off sc0 sc1
	v_cvt_pk_bf16_f32 v6, v26, v27
	v_cvt_pk_bf16_f32 v7, v28, v29
	v_cvt_pk_bf16_f32 v9, v4, v5
	v_lshl_add_u64 v[2:3], v[48:49], 0, v[36:37]
	global_store_dwordx4 v[2:3], v[6:9], off sc0 sc1
	s_waitcnt lgkmcnt(0)
	s_mov_b64 s[0:1], 0
.LBB0_17:
	s_andn2_b64 vcc, exec, s[0:1]
	s_cbranch_vccnz .LBB0_27
	s_add_i32 s0, s38, 0xfa80
	s_and_b32 s1, s0, 0xffff
	s_mul_i32 s1, s1, 0xba2f
	s_lshr_b32 s4, s1, 16
	s_lshr_b32 s1, s1, 22
	s_mulk_i32 s1, 0x58
	s_sub_i32 s0, s0, s1
	s_and_b32 s1, s0, 0xffff
	s_and_b32 s0, s4, 0xffc0
	v_or_b32_e32 v49, s0, v34
	s_lshl_b32 s6, s1, 7
	v_lshl_add_u64 v[2:3], v[44:45], 0, s[6:7]
	v_mul_u32_u24_e32 v36, 0x2c00, v49
	v_mad_u64_u32 v[4:5], s[4:5], v49, s29, v[2:3]
	v_lshl_add_u64 v[2:3], v[2:3], 0, v[36:37]
	v_add_co_u32_e32 v6, vcc, s30, v2
	v_cndmask_b32_e64 v36, 0, 1, s[8:9]
	s_nop 0
	v_addc_co_u32_e32 v7, vcc, 0, v3, vcc
	global_load_dwordx4 v[26:29], v[4:5], off nt
	global_load_dwordx4 v[30:33], v[6:7], off nt
	v_add_co_u32_e32 v4, vcc, s31, v2
	v_mov_b32_e32 v48, 1.0
	s_nop 0
	v_addc_co_u32_e32 v5, vcc, 0, v3, vcc
	v_add_co_u32_e32 v6, vcc, s36, v2
	v_cmp_ne_u32_e64 s[4:5], 1, v36
	s_nop 0
	v_addc_co_u32_e32 v7, vcc, 0, v3, vcc
	global_load_dwordx4 v[18:21], v[4:5], off nt
	global_load_dwordx4 v[22:25], v[6:7], off nt
	v_add_co_u32_e32 v4, vcc, s37, v2
	v_add_lshl_u32 v36, v34, s0, 2
	s_nop 0
	v_addc_co_u32_e32 v5, vcc, 0, v3, vcc
	v_add_co_u32_e32 v6, vcc, 0x6e000, v2
	v_mov_b32_e32 v60, 1.0
	s_nop 0
	v_addc_co_u32_e32 v7, vcc, 0, v3, vcc
	global_load_dwordx4 v[10:13], v[4:5], off nt
	global_load_dwordx4 v[14:17], v[6:7], off nt
	v_add_co_u32_e32 v4, vcc, 0x84000, v2
	s_nop 1
	v_addc_co_u32_e32 v5, vcc, 0, v3, vcc
	v_add_co_u32_e32 v6, vcc, 0x9a000, v2
	s_nop 1
	v_addc_co_u32_e32 v7, vcc, 0, v3, vcc
	global_load_dwordx4 v[2:5], v[4:5], off nt
	s_nop 0
	global_load_dwordx4 v[6:9], v[6:7], off nt
	s_andn2_b64 vcc, exec, s[8:9]
	s_cbranch_vccnz .LBB0_20
	v_lshlrev_b32_e32 v49, 2, v49
	global_load_dword v62, v49, s[72:73]
	global_load_dword v60, v36, s[72:73] offset:32
	s_waitcnt vmcnt(1)
	v_pk_mul_f32 v[26:27], v[26:27], v[62:63] op_sel_hi:[1,0]
	v_pk_mul_f32 v[28:29], v[28:29], v[62:63] op_sel_hi:[1,0]

.LBB0_28:
	s_andn2_b64 vcc, exec, s[0:1]
	s_cbranch_vccnz .LBB0_13
	s_mul_hi_i32 s0, s38, 0x2e8ba2e9
	s_lshr_b32 s1, s0, 31
	s_ashr_i32 s6, s0, 4
	s_add_i32 s6, s6, s1
	s_mul_i32 s0, s6, 0xfffff500
	s_lshl_b32 s4, s6, 6
	s_add_i32 s12, s14, s0
	v_or_b32_e32 v48, s4, v34
	s_ashr_i32 s13, s12, 31
	v_lshl_add_u64 v[2:3], s[12:13], 2, v[46:47]
	v_or_b32_e32 v6, 8, v48
	v_mad_i64_i32 v[4:5], s[0:1], v48, s29, v[2:3]
	v_mad_i64_i32 v[6:7], s[0:1], v6, s29, v[2:3]
	global_load_dwordx4 v[26:29], v[4:5], off nt
	global_load_dwordx4 v[30:33], v[6:7], off nt
	v_or_b32_e32 v4, 16, v48
	v_or_b32_e32 v6, 24, v48
	v_mad_i64_i32 v[4:5], s[0:1], v4, s29, v[2:3]
	v_mad_i64_i32 v[6:7], s[0:1], v6, s29, v[2:3]
	global_load_dwordx4 v[18:21], v[4:5], off nt
	global_load_dwordx4 v[22:25], v[6:7], off nt
	v_or_b32_e32 v4, 32, v48
	v_or_b32_e32 v6, 40, v48
	v_mad_i64_i32 v[4:5], s[0:1], v4, s29, v[2:3]
	v_mad_i64_i32 v[6:7], s[0:1], v6, s29, v[2:3]
	global_load_dwordx4 v[10:13], v[4:5], off nt
	global_load_dwordx4 v[14:17], v[6:7], off nt
	v_or_b32_e32 v4, 48, v48
	v_or_b32_e32 v6, 56, v48
	v_mad_i64_i32 v[4:5], s[0:1], v4, s29, v[2:3]
	v_mad_i64_i32 v[6:7], s[0:1], v6, s29, v[2:3]
	global_load_dwordx4 v[2:5], v[4:5], off nt
	s_nop 0
	global_load_dwordx4 v[6:9], v[6:7], off nt
	v_cndmask_b32_e64 v49, 0, 1, s[8:9]
	v_mov_b32_e32 v36, 1.0
	v_cmp_ne_u32_e64 s[0:1], 1, v49
	s_andn2_b64 vcc, exec, s[8:9]
	v_mov_b32_e32 v49, 1.0
	s_cbranch_vccnz .LBB0_31
	s_ashr_i32 s5, s4, 31
	v_ashrrev_i32_e32 v49, 31, v48
	v_lshl_add_u64 v[60:61], s[4:5], 0, v[34:35]
	v_lshl_add_u64 v[48:49], v[48:49], 2, s[72:73]
	v_lshl_add_u64 v[60:61], v[60:61], 2, s[72:73]
	global_load_dword v48, v[48:49], off
	s_nop 0
	global_load_dword v49, v[60:61], off offset:32
	s_waitcnt vmcnt(0)
	v_pk_mul_f32 v[26:27], v[26:27], v[48:49] op_sel_hi:[1,0]
	v_pk_mul_f32 v[28:29], v[28:29], v[48:49] op_sel_hi:[1,0]

.LBB0_44:
	s_ashr_i32 s13, s12, 31
	s_lshl_b64 s[0:1], s[12:13], 12
	v_lshl_add_u64 v[2:3], v[72:73], 0, s[0:1]
	global_load_dwordx4 v[22:25], v[2:3], off nt
	global_load_dwordx4 v[18:21], v[2:3], off offset:1024 nt
	s_waitcnt lgkmcnt(2)
	global_load_dwordx4 v[14:17], v[2:3], off offset:2048 nt
	s_waitcnt lgkmcnt(0)
	global_load_dwordx4 v[10:13], v[2:3], off offset:3072 nt
	s_add_i32 s0, s12, s11
	s_cmpk_lt_i32 s0, 0x4000
	s_cselect_b64 s[30:31], -1, 0
	s_and_b64 s[14:15], s[30:31], exec
	s_cselect_b32 s14, s0, s12
	s_ashr_i32 s15, s14, 31
	s_lshl_b64 s[14:15], s[14:15], 12
	v_lshl_add_u64 v[2:3], v[72:73], 0, s[14:15]
	global_load_dwordx4 v[38:41], v[2:3], off nt
	global_load_dwordx4 v[42:45], v[2:3], off offset:1024 nt
	global_load_dwordx4 v[34:37], v[2:3], off offset:2048 nt
	global_load_dwordx4 v[62:65], v[2:3], off offset:3072 nt
	s_add_i32 s16, s18, s12
	s_cmpk_lt_i32 s16, 0x4000
	s_cselect_b64 s[36:37], -1, 0
	s_and_b64 s[14:15], s[36:37], exec
	s_cselect_b32 s20, s16, s12
	s_ashr_i32 s21, s20, 31
	s_lshl_b64 s[20:21], s[20:21], 12
	v_lshl_add_u64 v[2:3], v[72:73], 0, s[20:21]
	global_load_dwordx4 v[58:61], v[2:3], off nt
	global_load_dwordx4 v[54:57], v[2:3], off offset:1024 nt
	global_load_dwordx4 v[50:53], v[2:3], off offset:2048 nt
	global_load_dwordx4 v[46:49], v[2:3], off offset:3072 nt
	s_add_i32 s14, s19, s12
	s_cmpk_lt_i32 s14, 0x4000
	s_cselect_b64 s[28:29], -1, 0
	s_and_b64 s[20:21], s[28:29], exec
	s_cselect_b32 s20, s14, s12
	s_ashr_i32 s21, s20, 31
	s_lshl_b64 s[20:21], s[20:21], 12
	v_lshl_add_u64 v[2:3], v[72:73], 0, s[20:21]
	global_load_dwordx4 v[30:33], v[2:3], off nt
	global_load_dwordx4 v[26:29], v[2:3], off offset:1024 nt
	global_load_dwordx4 v[6:9], v[2:3], off offset:2048 nt
	s_nop 0
	global_load_dwordx4 v[2:5], v[2:3], off offset:3072 nt
	v_mov_b32_e32 v67, 0
	v_mov_b32_e32 v82, 0
	v_mov_b32_e32 v83, 0
	s_lshl_b64 s[22:23], s[12:13], 11
	v_lshl_add_u64 v[80:81], v[68:69], 0, s[22:23]
	s_waitcnt vmcnt(15)
	v_mul_f32_e32 v84, v23, v23
	v_mul_f32_e32 v85, v25, v25
	s_waitcnt vmcnt(14)
	v_mul_f32_e32 v86, v19, v19
	v_mul_f32_e32 v87, v21, v21
	s_waitcnt vmcnt(13)
	v_mul_f32_e32 v88, v15, v15
	v_mul_f32_e32 v89, v17, v17
	v_fmac_f32_e32 v84, v22, v22
	v_fmac_f32_e32 v85, v24, v24
	v_fmac_f32_e32 v86, v18, v18
	v_fmac_f32_e32 v87, v20, v20
	v_cvt_pk_bf16_f32 v15, v14, v15
	v_cvt_pk_bf16_f32 v90, v16, v17
	s_waitcnt vmcnt(12)
	v_mul_f32_e32 v17, v11, v11
	v_mul_f32_e32 v91, v13, v13
	v_fmac_f32_e32 v88, v14, v14
	v_fmac_f32_e32 v89, v16, v16
	v_add_f32_e32 v14, v84, v85
	v_add_f32_e32 v16, v86, v87
	v_cvt_pk_bf16_f32 v19, v18, v19
	v_fmac_f32_e32 v17, v10, v10
	v_fmac_f32_e32 v91, v12, v12
	v_add_f32_e32 v18, v88, v89
	v_add_f32_e32 v14, v14, v16
	v_add_f32_e32 v17, v17, v91
	v_add_f32_e32 v14, v14, v18
	v_add_f32_e32 v14, v14, v17
	ds_bpermute_b32 v16, v74, v14
	v_cvt_pk_bf16_f32 v23, v22, v23
	v_cvt_pk_bf16_f32 v25, v24, v25
	v_cvt_pk_bf16_f32 v21, v20, v21
	v_cvt_pk_bf16_f32 v92, v10, v11
	v_cvt_pk_bf16_f32 v93, v12, v13
	v_cndmask_b32_e64 v11, v23, v19, s[6:7]
	v_cndmask_b32_e64 v13, v25, v21, s[6:7]
	v_cndmask_b32_e64 v10, v15, v92, s[6:7]
	v_mov_b32_dpp v67, v11 quad_perm:[1,0,3,2] row_mask:0xf bank_mask:0xf
	v_mov_b32_dpp v82, v13 quad_perm:[1,0,3,2] row_mask:0xf bank_mask:0xf
	v_mov_b32_dpp v83, v10 quad_perm:[1,0,3,2] row_mask:0xf bank_mask:0xf
	v_cndmask_b32_e64 v10, v67, v23, s[6:7]
	v_cndmask_b32_e64 v11, v82, v25, s[6:7]
	v_cndmask_b32_e64 v12, v19, v67, s[6:7]
	v_cndmask_b32_e64 v13, v21, v82, s[6:7]
	global_store_dwordx4 v[80:81], v[10:13], off sc0 sc1
	v_cndmask_b32_e64 v18, v83, v15, s[6:7]
	s_waitcnt vmcnt(11)
	v_mul_f32_e32 v15, v45, v45
	s_waitcnt lgkmcnt(0)
	v_add_f32_e32 v11, v14, v16
	ds_bpermute_b32 v12, v75, v11
	v_mul_f32_e32 v10, v39, v39
	v_mul_f32_e32 v13, v41, v41
	v_mul_f32_e32 v14, v43, v43
	s_waitcnt vmcnt(10)
	v_mul_f32_e32 v16, v35, v35
	s_waitcnt lgkmcnt(0)
	v_add_f32_e32 v11, v11, v12
	ds_bpermute_b32 v12, v76, v11
	v_mul_f32_e32 v17, v37, v37
	v_fmac_f32_e32 v10, v38, v38
	v_fmac_f32_e32 v13, v40, v40
	v_fmac_f32_e32 v14, v42, v42
	s_waitcnt lgkmcnt(0)
	v_add_f32_e32 v11, v11, v12
	ds_bpermute_b32 v12, v77, v11
	v_fmac_f32_e32 v15, v44, v44
	v_fmac_f32_e32 v16, v34, v34
	v_fmac_f32_e32 v17, v36, v36
	v_add_f32_e32 v10, v10, v13
	s_waitcnt lgkmcnt(0)
	v_add_f32_e32 v11, v11, v12
	ds_bpermute_b32 v12, v78, v11
	v_add_f32_e32 v13, v14, v15
	v_add_f32_e32 v14, v16, v17
	v_add_f32_e32 v10, v10, v13
	v_add_f32_e32 v10, v10, v14
	s_waitcnt lgkmcnt(0)
	v_add_f32_e32 v14, v11, v12
	s_waitcnt vmcnt(9)
	v_mul_f32_e32 v11, v63, v63
	v_mul_f32_e32 v12, v65, v65
	v_fmac_f32_e32 v11, v62, v62
	v_fmac_f32_e32 v12, v64, v64
	v_add_f32_e32 v11, v11, v12
	s_waitcnt vmcnt(8)
	v_mul_f32_e32 v12, v59, v59
	v_mul_f32_e32 v13, v61, v61
	v_fmac_f32_e32 v12, v58, v58
	v_fmac_f32_e32 v13, v60, v60
	v_add_f32_e32 v12, v12, v13
	s_waitcnt vmcnt(7)
	v_mul_f32_e32 v13, v55, v55
	v_mul_f32_e32 v16, v57, v57
	v_fmac_f32_e32 v13, v54, v54
	v_fmac_f32_e32 v16, v56, v56
	v_add_f32_e32 v13, v13, v16
	v_add_f32_e32 v12, v12, v13
	s_waitcnt vmcnt(6)
	v_mul_f32_e32 v13, v51, v51
	v_mul_f32_e32 v16, v53, v53
	v_fmac_f32_e32 v13, v50, v50
	v_fmac_f32_e32 v16, v52, v52
	v_add_f32_e32 v13, v13, v16
	v_add_f32_e32 v12, v12, v13
	s_waitcnt vmcnt(5)
	v_mul_f32_e32 v13, v47, v47
	v_mul_f32_e32 v16, v49, v49
	v_fmac_f32_e32 v13, v46, v46
	v_fmac_f32_e32 v16, v48, v48
	v_add_f32_e32 v13, v13, v16
	s_waitcnt vmcnt(4)
	v_mul_f32_e32 v16, v31, v31
	v_mul_f32_e32 v17, v33, v33
	v_fmac_f32_e32 v16, v30, v30
	v_fmac_f32_e32 v17, v32, v32
	v_add_f32_e32 v16, v16, v17
	s_waitcnt vmcnt(3)
	v_mul_f32_e32 v17, v27, v27
	v_mul_f32_e32 v22, v29, v29
	v_fmac_f32_e32 v17, v26, v26
	v_fmac_f32_e32 v22, v28, v28
	v_add_f32_e32 v17, v17, v22
	v_add_f32_e32 v16, v16, v17
	s_waitcnt vmcnt(2)
	v_mul_f32_e32 v17, v7, v7
	v_mul_f32_e32 v22, v9, v9
	v_fmac_f32_e32 v17, v6, v6
	v_fmac_f32_e32 v22, v8, v8
	v_add_f32_e32 v17, v17, v22
	v_add_f32_e32 v16, v16, v17
	s_waitcnt vmcnt(1)
	v_mul_f32_e32 v17, v3, v3
	v_mul_f32_e32 v22, v5, v5
	v_fmac_f32_e32 v17, v2, v2
	v_fmac_f32_e32 v22, v4, v4
	v_add_f32_e32 v17, v17, v22
	v_add_f32_e32 v10, v10, v11
	v_add_f32_e32 v12, v12, v13
	v_add_f32_e32 v16, v16, v17
	ds_bpermute_b32 v11, v74, v10
	ds_bpermute_b32 v13, v74, v12
	ds_bpermute_b32 v17, v74, v16
	ds_bpermute_b32 v15, v79, v14
	v_cndmask_b32_e64 v19, v90, v93, s[6:7]
	s_waitcnt lgkmcnt(3)
	v_add_f32_e32 v10, v10, v11
	s_waitcnt lgkmcnt(2)
	v_add_f32_e32 v12, v12, v13
	s_waitcnt lgkmcnt(1)
	v_add_f32_e32 v16, v16, v17
	ds_bpermute_b32 v11, v75, v10
	ds_bpermute_b32 v13, v75, v12
	ds_bpermute_b32 v17, v75, v16
	v_mov_b32_e32 v21, 0
	v_cndmask_b32_e64 v20, v92, v83, s[6:7]
	s_waitcnt lgkmcnt(2)
	v_add_f32_e32 v10, v10, v11
	s_waitcnt lgkmcnt(1)
	v_add_f32_e32 v12, v12, v13
	s_waitcnt lgkmcnt(0)
	v_add_f32_e32 v16, v16, v17
	ds_bpermute_b32 v11, v76, v10
	ds_bpermute_b32 v13, v76, v12
	ds_bpermute_b32 v17, v76, v16
	v_mov_b32_dpp v21, v19 quad_perm:[1,0,3,2] row_mask:0xf bank_mask:0xf
	v_cndmask_b32_e64 v19, v21, v90, s[6:7]
	s_waitcnt lgkmcnt(2)
	v_add_f32_e32 v10, v10, v11
	s_waitcnt lgkmcnt(1)
	v_add_f32_e32 v12, v12, v13
	s_waitcnt lgkmcnt(0)
	v_add_f32_e32 v16, v16, v17
	ds_bpermute_b32 v11, v77, v10
	ds_bpermute_b32 v13, v77, v12
	ds_bpermute_b32 v17, v77, v16
	v_cndmask_b32_e64 v21, v93, v21, s[6:7]
	global_store_dwordx4 v[80:81], v[18:21], off offset:1024 sc0 sc1
	s_waitcnt lgkmcnt(2)
	v_add_f32_e32 v10, v10, v11
	s_waitcnt lgkmcnt(1)
	v_add_f32_e32 v12, v12, v13
	s_waitcnt lgkmcnt(0)
	v_add_f32_e32 v22, v16, v17
	ds_bpermute_b32 v11, v78, v10
	ds_bpermute_b32 v13, v78, v12
	ds_bpermute_b32 v23, v78, v22
	s_waitcnt lgkmcnt(2)
	v_add_f32_e32 v16, v10, v11
	s_waitcnt lgkmcnt(1)
	v_add_f32_e32 v12, v12, v13
	s_waitcnt lgkmcnt(0)
	v_add_f32_e32 v10, v22, v23
	ds_bpermute_b32 v17, v79, v16
	ds_bpermute_b32 v13, v79, v12
	ds_bpermute_b32 v11, v79, v10
	s_and_saveexec_b64 s[38:39], s[4:5]
	s_cbranch_execnz .LBB0_48
	s_or_b64 exec, exec, s[38:39]
	s_andn2_b64 vcc, exec, s[30:31]
	s_cbranch_vccz .LBB0_49

.LBB0_57:
	s_cmp_lt_i32 s10, 16
	s_cbranch_scc0 .LBB0_61
	s_ashr_i32 s11, s10, 31
	s_lshl_b64 s[0:1], s[10:11], 12
	s_add_u32 s0, s70, s0
	s_addc_u32 s1, s71, s1
	global_load_dwordx4 v[4:7], v66, s[0:1] nt
	s_waitcnt lgkmcnt(0)
	global_load_dwordx4 v[8:11], v66, s[0:1] offset:1024 nt
	global_load_dwordx4 v[12:15], v66, s[0:1] offset:2048 nt
	global_load_dwordx4 v[16:19], v66, s[0:1] offset:3072 nt
	v_mbcnt_lo_u32_b32 v20, -1, 0
	v_mbcnt_hi_u32_b32 v20, -1, v20
	v_and_b32_e32 v21, 64, v20
	v_xor_b32_e32 v22, 1, v20
	v_add_u32_e32 v21, 64, v21
	v_xor_b32_e32 v23, 2, v20
	v_cmp_lt_i32_e32 vcc, v22, v21
	v_xor_b32_e32 v24, 4, v20
	v_xor_b32_e32 v25, 8, v20
	v_cndmask_b32_e32 v22, v20, v22, vcc
	v_cmp_lt_i32_e32 vcc, v23, v21
	v_xor_b32_e32 v26, 16, v20
	v_xor_b32_e32 v27, 32, v20
	v_cndmask_b32_e32 v23, v20, v23, vcc
	v_cmp_lt_i32_e32 vcc, v24, v21
	v_lshlrev_b32_e32 v23, 2, v23
	s_lshl_b64 s[4:5], s[10:11], 11
	v_cndmask_b32_e32 v24, v20, v24, vcc
	v_cmp_lt_i32_e32 vcc, v25, v21
	s_add_u32 s4, s86, s4
	v_mov_b32_e32 v3, 0
	v_cndmask_b32_e32 v25, v20, v25, vcc
	v_cmp_lt_i32_e32 vcc, v26, v21
	v_lshlrev_b32_e32 v2, 3, v1
	s_addc_u32 s5, s87, s5
	v_cndmask_b32_e32 v26, v20, v26, vcc
	v_cmp_lt_i32_e32 vcc, v27, v21
	v_lshlrev_b32_e32 v21, 2, v22
	v_lshlrev_b32_e32 v24, 2, v24
	v_cndmask_b32_e32 v20, v20, v27, vcc
	v_lshlrev_b32_e32 v25, 2, v25
	v_lshlrev_b32_e32 v26, 2, v26
	s_mov_b64 s[0:1], 0x10b000
	s_mov_b32 s6, 0x10b000
	s_waitcnt vmcnt(3)
	v_mul_f32_e32 v22, v5, v5
	v_mul_f32_e32 v27, v7, v7
	s_waitcnt vmcnt(2)
	v_mul_f32_e32 v28, v9, v9
	v_mul_f32_e32 v29, v11, v11
	s_waitcnt vmcnt(1)
	v_mul_f32_e32 v30, v13, v13
	v_mul_f32_e32 v31, v15, v15
	v_fmac_f32_e32 v22, v4, v4
	v_fmac_f32_e32 v27, v6, v6
	v_fmac_f32_e32 v28, v8, v8
	v_fmac_f32_e32 v29, v10, v10
	s_waitcnt vmcnt(0)
	v_mul_f32_e32 v32, v17, v17
	v_mul_f32_e32 v33, v19, v19
	v_fmac_f32_e32 v30, v12, v12
	v_fmac_f32_e32 v31, v14, v14
	v_add_f32_e32 v22, v22, v27
	v_add_f32_e32 v27, v28, v29
	v_fmac_f32_e32 v32, v16, v16
	v_fmac_f32_e32 v33, v18, v18
	v_add_f32_e32 v28, v30, v31
	v_add_f32_e32 v22, v22, v27
	v_add_f32_e32 v29, v32, v33
	v_add_f32_e32 v22, v22, v28
	v_add_f32_e32 v22, v22, v29
	ds_bpermute_b32 v21, v21, v22
	v_lshlrev_b32_e32 v29, 2, v20
	v_cvt_pk_bf16_f32 v4, v4, v5
	v_cvt_pk_bf16_f32 v5, v6, v7
	v_cvt_pk_bf16_f32 v7, v10, v11
	s_waitcnt lgkmcnt(0)
	v_add_f32_e32 v27, v22, v21
	ds_bpermute_b32 v28, v23, v27
	v_lshl_add_u64 v[20:21], s[4:5], 0, v[2:3]
	v_lshl_add_u64 v[22:23], v[20:21], 0, s[0:1]
	v_add_co_u32_e32 v20, vcc, s6, v20
	s_waitcnt lgkmcnt(0)
	v_add_f32_e32 v2, v27, v28
	ds_bpermute_b32 v24, v24, v2
	v_addc_co_u32_e32 v21, vcc, 0, v21, vcc
	v_cvt_pk_bf16_f32 v6, v8, v9
	global_store_dwordx2 v[20:21], v[4:5], off
	global_store_dwordx2 v[22:23], v[6:7], off offset:512
	s_waitcnt lgkmcnt(0)
	v_add_f32_e32 v2, v2, v24
	ds_bpermute_b32 v24, v25, v2
	v_cvt_pk_bf16_f32 v8, v12, v13
	v_cvt_pk_bf16_f32 v9, v14, v15
	v_cvt_pk_bf16_f32 v6, v16, v17
	v_cvt_pk_bf16_f32 v7, v18, v19
	s_waitcnt lgkmcnt(0)
	v_add_f32_e32 v2, v2, v24
	ds_bpermute_b32 v10, v26, v2
	v_cmp_gt_u32_e32 vcc, 16, v1
	global_store_dwordx2 v[22:23], v[8:9], off offset:1024
	global_store_dwordx2 v[22:23], v[6:7], off offset:1536
	s_waitcnt lgkmcnt(0)
	v_add_f32_e32 v2, v2, v10
	ds_bpermute_b32 v4, v29, v2
	s_and_saveexec_b64 s[0:1], vcc
	s_cbranch_execz .LBB0_60
	s_lshl_b32 s4, s10, 4
	s_ashr_i32 s5, s4, 31
	s_lshl_b64 s[4:5], s[4:5], 2
	s_waitcnt lgkmcnt(0)
	v_add_f32_e32 v2, v2, v4
	v_cmp_eq_u32_e32 vcc, 0, v1
	s_add_u32 s4, s86, s4
	s_addc_u32 s5, s87, s5
	v_cndmask_b32_e32 v4, 0, v2, vcc
	v_lshlrev_b32_e32 v2, 2, v1
	v_lshl_add_u64 v[2:3], s[4:5], 0, v[2:3]
	v_add_co_u32_e32 v2, vcc, 0x113000, v2
	s_nop 1
	v_addc_co_u32_e32 v3, vcc, 0, v3, vcc
	global_store_dword v[2:3], v4, off
